# PROJ epilogue: diff-RoPE cos/sin rows of the tile staged into LDS scratch once; per-step table loads + vmcnt(0) become ds_read + lgkmcnt(0)
# speedup vs baseline: 1.0096x; 1.0096x over previous
;     __device__ __forceinline__ void operator()(const f32x4 (&acc)[2][2][4][2], const Unit& u, int wr, int wc, int fr, int fq) const {
;         const int colt = u.pn * BM;
;         const int row0 = u.pm * BM + wr * 64 + fr;
;         const int region = colt < 2048 ? 0 : colt < 3072 ? 1 : colt < 5120 ? 2 : colt < 6144 ? 1 : 3;
;         const float qs = colt < 1024 ? 0.125f * LOG2E : (colt >= 3072 && colt < 4096) ? 0.08838834764831845f * LOG2E : 1.0f;
;         const bool kmt = colt >= 4096 && colt < 5120;
;         if (region == 1) {
;     ...
;                     if (region == 0) {
;                         if ((wc & 1) == 0) {
;                             float pr[8];
; #pragma unroll
;                             for (int e = 0; e < 8; ++e) pr[e] = __shfl_xor(v[e], 16);
;                             if (fq < 2) {
;                                 const f32x4* cp = (const f32x4*)(csd + pos * 16);
;                                 const f32x4 c0 = cp[0], c1 = cp[1], s0 = cp[2], s1 = cp[3];
;                                 const float cs[8] = {c0[0], c0[1], c0[2], c0[3], c1[0], c1[1], c1[2], c1[3]};
;                                 const float sn[8] = {s0[0], s0[1], s0[2], s0[3], s1[0], s1[1], s1[2], s1[3]};
;                                 const float sg = fq == 0 ? -1.f : 1.f;
; #pragma unroll
;                                 for (int e = 0; e < 8; ++e) v[e] = v[e] * cs[e] + sg * pr[e] * sn[e];
;                             }
;                         }
; #pragma unroll
;                         for (int e = 0; e < 8; ++e) v[e] *= qs;
;                     } else if (region == 2) {
;                         if (wc == 0) {
;                             float pr[8];
; #pragma unroll
;                             for (int e = 0; e < 8; ++e) pr[e] = __shfl_xor(v[e], 32);
;                             const f32x4* cp = (const f32x4*)(csm + pos * 32 + (fq & 1) * 8);
;                             const f32x4 c0 = cp[0], c1 = cp[1], s0 = cp[4], s1 = cp[5];
;                             const float cs[8] = {c0[0], c0[1], c0[2], c0[3], c1[0], c1[1], c1[2], c1[3]};
;                             const float sn[8] = {s0[0], s0[1], s0[2], s0[3], s1[0], s1[1], s1[2], s1[3]};
;                             const float sg = fq < 2 ? -1.f : 1.f;
; #pragma unroll
;                             for (int e = 0; e < 8; ++e) v[e] = v[e] * cs[e] + sg * pr[e] * sn[e];
.LBB0_325:
	s_lshl_b32 s1, s88, 8
	s_lshl_b32 s43, s90, 8
	s_add_i32 s1, s1, s74
	s_cmp_lt_u32 s90, 24
	s_cselect_b32 s4, 1, 3
	s_cmp_gt_u32 s90, 19
	s_cselect_b32 s4, s4, 2
	s_cmp_gt_u32 s90, 11
	s_cselect_b32 s4, s4, 1
	s_cmp_gt_i32 s90, 7
	s_cselect_b32 s45, s4, 0
	s_cmp_lg_u32 s45, 0
	s_cbranch_scc1 .Lproj_nostage
	s_and_b32 s98, s88, 15
	s_lshl_b32 s98, s98, 14
	v_lshlrev_b32_e32 v156, 5, v202
	v_add_u32_e32 v157, s98, v156
	global_load_dwordx4 v[164:167], v157, s[80:81]
	global_load_dwordx4 v[168:171], v157, s[80:81] offset:16
	v_add_u32_e32 v156, 0x20080, v156
	s_sub_i32 s98, 0x20080, s98
	s_waitcnt vmcnt(0)
	ds_write_b128 v156, v[164:167]
	ds_write_b128 v156, v[168:171] offset:16
	s_waitcnt lgkmcnt(0)
	s_barrier
.Lproj_nostage:
	s_cmp_lg_u32 s45, 1
	s_mov_b64 s[4:5], -1
	s_cbranch_scc0 .LBB0_334
	s_and_b32 s4, s90, 0x7ffffffc
	s_cmp_eq_u32 s4, 12
	s_cselect_b64 vcc, -1, 0
	s_cmp_gt_i32 s90, 3
	s_cselect_b64 s[14:15], -1, 0
	s_and_b32 s4, s90, -4
	s_cmp_eq_u32 s4, 16
	s_cselect_b64 s[54:55], -1, 0
	s_cmp_gt_i32 s45, 2
	s_mov_b64 s[4:5], -1
	s_cbranch_scc0 .LBB0_328
	v_mul_f32_e32 v154, 0xbfb8aa3b, v124
	v_exp_f32_e32 v154, v154
	v_mul_f32_e32 v155, 0xbfb8aa3b, v125
	v_exp_f32_e32 v155, v155
	v_mul_f32_e32 v156, 0xbfb8aa3b, v127
	v_add_f32_e32 v154, 1.0, v154
	v_rcp_f32_e32 v166, v154
	v_mul_f32_e32 v154, 0xbfb8aa3b, v126
	v_exp_f32_e32 v154, v154
	v_exp_f32_e32 v156, v156
	v_add_f32_e32 v155, 1.0, v155
	v_rcp_f32_e32 v167, v155
	v_add_f32_e32 v154, 1.0, v154
	v_mul_f32_e32 v155, 0xbfb8aa3b, v120
	v_rcp_f32_e32 v172, v154
	v_add_f32_e32 v154, 1.0, v156
	v_exp_f32_e32 v155, v155
	v_mul_f32_e32 v156, 0xbfb8aa3b, v121
	v_exp_f32_e32 v156, v156
	v_rcp_f32_e32 v173, v154
	v_add_f32_e32 v154, 1.0, v155
	v_mul_f32_e32 v155, 0xbfb8aa3b, v122
	v_rcp_f32_e32 v176, v154
	v_add_f32_e32 v154, 1.0, v156
	v_exp_f32_e32 v155, v155
	v_mul_f32_e32 v156, 0xbfb8aa3b, v123
	v_exp_f32_e32 v156, v156
	v_rcp_f32_e32 v177, v154
	v_add_f32_e32 v154, 1.0, v155
	v_rcp_f32_e32 v178, v154
	v_add_f32_e32 v154, 1.0, v156
	v_rcp_f32_e32 v179, v154
	s_mov_b64 s[4:5], 0
.LBB0_328:
	v_bitop3_b32 v154, s1, v216, v137 bitop3:0xc8
	v_lshlrev_b32_e32 v192, 5, v154
	v_lshlrev_b32_e32 v155, 4, v154
	v_cndmask_b32_e32 v154, 1.0, v217, vcc
	s_andn2_b64 vcc, exec, s[4:5]
	v_cndmask_b32_e64 v154, v218, v154, s[14:15]
	s_cbranch_vccnz .LBB0_352
	s_cmp_lg_u32 s45, 2
	s_mov_b64 s[4:5], -1
	s_cbranch_scc0 .LBB0_355
	s_andn2_b64 vcc, exec, s[86:87]
	s_cbranch_vccnz .LBB0_353
	v_and_b32_e32 v157, 64, v210
	v_xor_b32_e32 v156, 16, v210
	v_add_u32_e32 v157, 64, v157
	v_cmp_lt_i32_e32 vcc, v156, v157
	v_mov_b32_e32 v167, v123
	v_mov_b32_e32 v166, v122
	v_cndmask_b32_e32 v156, v210, v156, vcc
	v_lshlrev_b32_e32 v156, 2, v156
	ds_bpermute_b32 v173, v156, v124
	ds_bpermute_b32 v174, v156, v125
	ds_bpermute_b32 v171, v156, v126
	ds_bpermute_b32 v172, v156, v127
	ds_bpermute_b32 v169, v156, v120
	ds_bpermute_b32 v170, v156, v121
	ds_bpermute_b32 v168, v156, v122
	ds_bpermute_b32 v160, v156, v123
	v_mov_b32_e32 v165, v121
	v_mov_b32_e32 v164, v120
	v_mov_b32_e32 v159, v127
	v_mov_b32_e32 v158, v126
	v_mov_b32_e32 v157, v125
	v_mov_b32_e32 v156, v124
	s_and_saveexec_b64 s[4:5], s[6:7]
	s_cbranch_execz .LBB0_333
	v_lshl_add_u32 v175, v155, 2, s98
	ds_read_b128 v[156:159], v175
	ds_read_b128 v[164:167], v175 offset:16
	ds_read_b128 v[176:179], v175 offset:48
	ds_read_b128 v[180:183], v175 offset:32
	s_waitcnt lgkmcnt(0)
	v_cndmask_b32_e64 v168, v168, -v168, s[10:11]
	v_cndmask_b32_e64 v184, v173, -v173, s[10:11]
	v_cndmask_b32_e64 v175, v172, -v172, s[10:11]
	v_cndmask_b32_e64 v172, v169, -v169, s[10:11]
	v_cndmask_b32_e64 v173, v170, -v170, s[10:11]
	v_cndmask_b32_e64 v169, v160, -v160, s[10:11]
	v_cndmask_b32_e64 v185, v174, -v174, s[10:11]
	v_cndmask_b32_e64 v174, v171, -v171, s[10:11]
	s_waitcnt lgkmcnt(0)
	v_pk_mul_f32 v[158:159], v[126:127], v[158:159]
	v_pk_mul_f32 v[156:157], v[124:125], v[156:157]
	v_mul_f32_e32 v170, v168, v178
	v_mov_b32_e32 v178, v123
	v_mov_b32_e32 v168, v167
	v_pk_mul_f32 v[168:169], v[178:179], v[168:169]
	v_pk_mul_f32 v[164:165], v[120:121], v[164:165]
	v_mul_f32_e32 v166, v122, v166
	v_mov_b32_e32 v167, v168
	v_mov_b32_e32 v171, v169
	v_pk_fma_f32 v[156:157], v[184:185], v[180:181], v[156:157]
	v_pk_fma_f32 v[158:159], v[174:175], v[182:183], v[158:159]
	v_pk_fma_f32 v[164:165], v[172:173], v[176:177], v[164:165]
	v_pk_add_f32 v[166:167], v[166:167], v[170:171]

;     __device__ __forceinline__ void operator()(const f32x4 (&acc)[2][2][4][2], const Unit& u, int wr, int wc, int fr, int fq) const {
;     ...
;                             if (fq < 2) {
;                                 const f32x4* cp = (const f32x4*)(csd + pos * 16);
;                                 const f32x4 c0 = cp[0], c1 = cp[1], s0 = cp[2], s1 = cp[3];
;                                 const float cs[8] = {c0[0], c0[1], c0[2], c0[3], c1[0], c1[1], c1[2], c1[3]};
;                                 const float sn[8] = {s0[0], s0[1], s0[2], s0[3], s1[0], s1[1], s1[2], s1[3]};
;                                 const float sg = fq == 0 ? -1.f : 1.f;
; #pragma unroll
;                                 for (int e = 0; e < 8; ++e) v[e] = v[e] * cs[e] + sg * pr[e] * sn[e];
.LBB0_376:
	s_andn2_b64 vcc, exec, s[4:5]
	s_cbranch_vccnz .LBB0_386
	s_cmp_lg_u32 s45, 1
	s_cbranch_scc0 .LBB0_382
	s_andn2_b64 vcc, exec, s[86:87]
	s_cbranch_vccnz .LBB0_383
	v_and_b32_e32 v160, 64, v210
	v_xor_b32_e32 v159, 16, v210
	v_add_u32_e32 v160, 64, v160
	v_cmp_lt_i32_e32 vcc, v159, v160
	v_mov_b32_e32 v179, v91
	v_mov_b32_e32 v178, v90
	v_cndmask_b32_e32 v159, v210, v159, vcc
	v_lshlrev_b32_e32 v159, 2, v159
	ds_bpermute_b32 v188, v159, v92
	ds_bpermute_b32 v189, v159, v93
	ds_bpermute_b32 v184, v159, v94
	ds_bpermute_b32 v185, v159, v95
	ds_bpermute_b32 v180, v159, v88
	ds_bpermute_b32 v181, v159, v89
	ds_bpermute_b32 v160, v159, v90
	ds_bpermute_b32 v159, v159, v91
	v_mov_b32_e32 v177, v89
	v_mov_b32_e32 v176, v88
	v_mov_b32_e32 v173, v95
	v_mov_b32_e32 v172, v94
	v_mov_b32_e32 v167, v93
	v_mov_b32_e32 v166, v92
	s_and_saveexec_b64 s[4:5], s[6:7]
	s_cbranch_execz .LBB0_381
	v_lshl_add_u32 v155, v155, 2, s98
	ds_read_b128 v[176:179], v155
	ds_read_b128 v[190:193], v155 offset:16
	ds_read_b128 v[194:197], v155 offset:48
	ds_read_b128 v[222:225], v155 offset:32
	s_waitcnt lgkmcnt(0)
	v_cndmask_b32_e64 v155, v160, -v160, s[10:11]
	v_cndmask_b32_e64 v166, v188, -v188, s[10:11]
	v_cndmask_b32_e64 v167, v189, -v189, s[10:11]
	v_cndmask_b32_e64 v172, v184, -v184, s[10:11]
	v_cndmask_b32_e64 v173, v185, -v185, s[10:11]
	v_cndmask_b32_e64 v185, v159, -v159, s[10:11]
	v_cndmask_b32_e64 v180, v180, -v180, s[10:11]
	v_cndmask_b32_e64 v181, v181, -v181, s[10:11]
	s_waitcnt lgkmcnt(0)
	v_pk_mul_f32 v[178:179], v[94:95], v[178:179]
	v_pk_mul_f32 v[188:189], v[88:89], v[190:191]
	v_mul_f32_e32 v190, v90, v192
	v_mul_f32_e32 v192, v155, v196
	v_mov_b32_e32 v196, v91
	v_mov_b32_e32 v184, v193
	v_pk_mul_f32 v[184:185], v[196:197], v[184:185]
	v_pk_mul_f32 v[176:177], v[92:93], v[176:177]
	v_mov_b32_e32 v191, v184
	v_mov_b32_e32 v193, v185
	v_pk_fma_f32 v[166:167], v[166:167], v[222:223], v[176:177]
	v_pk_fma_f32 v[172:173], v[172:173], v[224:225], v[178:179]
	v_pk_fma_f32 v[176:177], v[180:181], v[194:195], v[188:189]
	v_pk_add_f32 v[178:179], v[190:191], v[192:193]

;     __device__ __forceinline__ void operator()(const f32x4 (&acc)[2][2][4][2], const Unit& u, int wr, int wc, int fr, int fq) const {
;     ...
;                             if (fq < 2) {
;                                 const f32x4* cp = (const f32x4*)(csd + pos * 16);
;                                 const f32x4 c0 = cp[0], c1 = cp[1], s0 = cp[2], s1 = cp[3];
;                                 const float cs[8] = {c0[0], c0[1], c0[2], c0[3], c1[0], c1[1], c1[2], c1[3]};
;                                 const float sn[8] = {s0[0], s0[1], s0[2], s0[3], s1[0], s1[1], s1[2], s1[3]};
;                                 const float sg = fq == 0 ? -1.f : 1.f;
; #pragma unroll
;                                 for (int e = 0; e < 8; ++e) v[e] = v[e] * cs[e] + sg * pr[e] * sn[e];
.LBB0_399:
	s_andn2_b64 vcc, exec, s[4:5]
	v_lshlrev_b32_e32 v159, 4, v159
	s_cbranch_vccnz .LBB0_409
	s_cmp_lg_u32 s45, 1
	s_cbranch_scc0 .LBB0_405
	s_andn2_b64 vcc, exec, s[86:87]
	s_cbranch_vccnz .LBB0_406
	v_and_b32_e32 v164, 64, v210
	v_xor_b32_e32 v160, 16, v210
	v_add_u32_e32 v164, 64, v164
	v_cmp_lt_i32_e32 vcc, v160, v164
	v_mov_b32_e32 v185, v115
	v_mov_b32_e32 v184, v114
	v_cndmask_b32_e32 v160, v210, v160, vcc
	v_lshlrev_b32_e32 v160, 2, v160
	ds_bpermute_b32 v193, v160, v116
	ds_bpermute_b32 v194, v160, v117
	ds_bpermute_b32 v191, v160, v118
	ds_bpermute_b32 v192, v160, v119
	ds_bpermute_b32 v189, v160, v112
	ds_bpermute_b32 v190, v160, v113
	ds_bpermute_b32 v188, v160, v114
	ds_bpermute_b32 v160, v160, v115
	v_mov_b32_e32 v181, v113
	v_mov_b32_e32 v180, v112
	v_mov_b32_e32 v171, v119
	v_mov_b32_e32 v170, v118
	v_mov_b32_e32 v165, v117
	v_mov_b32_e32 v164, v116
	s_and_saveexec_b64 s[4:5], s[6:7]
	s_cbranch_execz .LBB0_404
	v_lshl_add_u32 v164, v159, 2, s98
	ds_read_b128 v[196:199], v164
	ds_read_b128 v[222:225], v164 offset:16
	ds_read_b128 v[226:229], v164 offset:48
	ds_read_b128 v[230:233], v164 offset:32
	s_waitcnt lgkmcnt(0)
	v_cndmask_b32_e64 v184, v188, -v188, s[10:11]
	v_cndmask_b32_e64 v170, v191, -v191, s[10:11]
	v_cndmask_b32_e64 v181, v190, -v190, s[10:11]
	v_cndmask_b32_e64 v185, v160, -v160, s[10:11]
	v_cndmask_b32_e64 v164, v193, -v193, s[10:11]
	v_cndmask_b32_e64 v165, v194, -v194, s[10:11]
	v_cndmask_b32_e64 v171, v192, -v192, s[10:11]
	v_cndmask_b32_e64 v180, v189, -v189, s[10:11]
	s_waitcnt lgkmcnt(0)
	v_pk_mul_f32 v[190:191], v[116:117], v[196:197]
	v_pk_mul_f32 v[188:189], v[118:119], v[198:199]
	v_mul_f32_e32 v196, v184, v228
	v_mov_b32_e32 v228, v115
	v_mov_b32_e32 v184, v225
	v_pk_mul_f32 v[184:185], v[228:229], v[184:185]
	v_pk_mul_f32 v[192:193], v[112:113], v[222:223]
	v_mul_f32_e32 v194, v114, v224
	v_mov_b32_e32 v195, v184
	v_mov_b32_e32 v197, v185
	v_pk_fma_f32 v[164:165], v[164:165], v[230:231], v[190:191]
	v_pk_fma_f32 v[170:171], v[170:171], v[232:233], v[188:189]
	v_pk_fma_f32 v[180:181], v[180:181], v[226:227], v[192:193]
	v_pk_add_f32 v[184:185], v[194:195], v[196:197]

;     __device__ __forceinline__ void operator()(const f32x4 (&acc)[2][2][4][2], const Unit& u, int wr, int wc, int fr, int fq) const {
;     ...
;                             if (fq < 2) {
;                                 const f32x4* cp = (const f32x4*)(csd + pos * 16);
;                                 const f32x4 c0 = cp[0], c1 = cp[1], s0 = cp[2], s1 = cp[3];
;                                 const float cs[8] = {c0[0], c0[1], c0[2], c0[3], c1[0], c1[1], c1[2], c1[3]};
;                                 const float sn[8] = {s0[0], s0[1], s0[2], s0[3], s1[0], s1[1], s1[2], s1[3]};
;                                 const float sg = fq == 0 ? -1.f : 1.f;
; #pragma unroll
;                                 for (int e = 0; e < 8; ++e) v[e] = v[e] * cs[e] + sg * pr[e] * sn[e];
.LBB0_425:
	s_cmp_lg_u32 s45, 1
	s_cbranch_scc0 .LBB0_430
	s_andn2_b64 vcc, exec, s[86:87]
	s_cbranch_vccnz .LBB0_431
	v_and_b32_e32 v160, 64, v210
	v_xor_b32_e32 v155, 16, v210
	v_add_u32_e32 v160, 64, v160
	v_cmp_lt_i32_e32 vcc, v155, v160
	v_mov_b32_e32 v189, v83
	v_mov_b32_e32 v188, v82
	v_cndmask_b32_e32 v155, v210, v155, vcc
	v_lshlrev_b32_e32 v155, 2, v155
	ds_bpermute_b32 v196, v155, v84
	ds_bpermute_b32 v197, v155, v85
	ds_bpermute_b32 v194, v155, v86
	ds_bpermute_b32 v195, v155, v87
	ds_bpermute_b32 v192, v155, v80
	ds_bpermute_b32 v193, v155, v81
	ds_bpermute_b32 v160, v155, v82
	ds_bpermute_b32 v155, v155, v83
	v_mov_b32_e32 v183, v81
	v_mov_b32_e32 v182, v80
	v_mov_b32_e32 v175, v87
	v_mov_b32_e32 v174, v86
	v_mov_b32_e32 v169, v85
	v_mov_b32_e32 v168, v84
	s_and_saveexec_b64 s[4:5], s[6:7]
	s_cbranch_execz .LBB0_429
	v_lshl_add_u32 v159, v159, 2, s98
	ds_read_b128 v[222:225], v159
	ds_read_b128 v[226:229], v159 offset:16
	ds_read_b128 v[230:233], v159 offset:48
	ds_read_b128 v[234:237], v159 offset:32
	s_waitcnt lgkmcnt(0)
	v_cndmask_b32_e64 v159, v160, -v160, s[10:11]
	v_cndmask_b32_e64 v174, v194, -v194, s[10:11]
	v_cndmask_b32_e64 v175, v195, -v195, s[10:11]
	v_cndmask_b32_e64 v189, v155, -v155, s[10:11]
	v_cndmask_b32_e64 v168, v196, -v196, s[10:11]
	v_cndmask_b32_e64 v169, v197, -v197, s[10:11]
	v_cndmask_b32_e64 v182, v192, -v192, s[10:11]
	v_cndmask_b32_e64 v183, v193, -v193, s[10:11]
	s_waitcnt lgkmcnt(0)
	v_pk_mul_f32 v[194:195], v[84:85], v[222:223]
	v_mov_b32_e32 v188, v229
	v_mul_f32_e32 v222, v159, v232
	v_mov_b32_e32 v232, v83
	v_pk_mul_f32 v[188:189], v[232:233], v[188:189]
	v_pk_mul_f32 v[192:193], v[86:87], v[224:225]
	v_pk_mul_f32 v[196:197], v[80:81], v[226:227]
	v_mul_f32_e32 v198, v82, v228
	v_mov_b32_e32 v199, v188
	v_mov_b32_e32 v223, v189
	v_pk_fma_f32 v[168:169], v[168:169], v[234:235], v[194:195]
	v_pk_fma_f32 v[174:175], v[174:175], v[236:237], v[192:193]
	v_pk_fma_f32 v[182:183], v[182:183], v[230:231], v[196:197]
	v_pk_add_f32 v[188:189], v[198:199], v[222:223]

;     __device__ __forceinline__ void operator()(const f32x4 (&acc)[2][2][4][2], const Unit& u, int wr, int wc, int fr, int fq) const {
;     ...
;                             if (fq < 2) {
;                                 const f32x4* cp = (const f32x4*)(csd + pos * 16);
;                                 const f32x4 c0 = cp[0], c1 = cp[1], s0 = cp[2], s1 = cp[3];
;                                 const float cs[8] = {c0[0], c0[1], c0[2], c0[3], c1[0], c1[1], c1[2], c1[3]};
;                                 const float sn[8] = {s0[0], s0[1], s0[2], s0[3], s1[0], s1[1], s1[2], s1[3]};
;                                 const float sg = fq == 0 ? -1.f : 1.f;
; #pragma unroll
;                                 for (int e = 0; e < 8; ++e) v[e] = v[e] * cs[e] + sg * pr[e] * sn[e];
.LBB0_445:
	s_andn2_b64 vcc, exec, s[4:5]
	v_lshlrev_b32_e32 v159, 4, v159
	s_cbranch_vccnz .LBB0_455
	s_cmp_lg_u32 s45, 1
	s_cbranch_scc0 .LBB0_451
	s_andn2_b64 vcc, exec, s[86:87]
	s_cbranch_vccnz .LBB0_452
	v_and_b32_e32 v166, 64, v210
	v_xor_b32_e32 v160, 16, v210
	v_add_u32_e32 v166, 64, v166
	v_cmp_lt_i32_e32 vcc, v160, v166
	v_mov_b32_e32 v179, v107
	v_mov_b32_e32 v178, v106
	v_cndmask_b32_e32 v160, v210, v160, vcc
	v_lshlrev_b32_e32 v160, 2, v160
	ds_bpermute_b32 v193, v160, v108
	ds_bpermute_b32 v194, v160, v109
	ds_bpermute_b32 v191, v160, v110
	ds_bpermute_b32 v192, v160, v111
	ds_bpermute_b32 v187, v160, v104
	ds_bpermute_b32 v190, v160, v105
	ds_bpermute_b32 v186, v160, v106
	ds_bpermute_b32 v160, v160, v107
	v_mov_b32_e32 v177, v105
	v_mov_b32_e32 v176, v104
	v_mov_b32_e32 v173, v111
	v_mov_b32_e32 v172, v110
	v_mov_b32_e32 v167, v109
	v_mov_b32_e32 v166, v108
	s_and_saveexec_b64 s[4:5], s[6:7]
	s_cbranch_execz .LBB0_450
	v_lshl_add_u32 v166, v159, 2, s98
	ds_read_b128 v[176:179], v166
	ds_read_b128 v[196:199], v166 offset:16
	ds_read_b128 v[222:225], v166 offset:48
	ds_read_b128 v[226:229], v166 offset:32
	s_waitcnt lgkmcnt(0)
	v_cndmask_b32_e64 v186, v186, -v186, s[10:11]
	v_cndmask_b32_e64 v166, v193, -v193, s[10:11]
	v_cndmask_b32_e64 v172, v191, -v191, s[10:11]
	v_cndmask_b32_e64 v173, v192, -v192, s[10:11]
	v_cndmask_b32_e64 v192, v187, -v187, s[10:11]
	v_cndmask_b32_e64 v193, v190, -v190, s[10:11]
	v_cndmask_b32_e64 v187, v160, -v160, s[10:11]
	v_cndmask_b32_e64 v167, v194, -v194, s[10:11]
	s_waitcnt lgkmcnt(0)
	v_pk_mul_f32 v[178:179], v[110:111], v[178:179]
	v_pk_mul_f32 v[190:191], v[104:105], v[196:197]
	v_mul_f32_e32 v196, v186, v224
	v_mov_b32_e32 v224, v107
	v_mov_b32_e32 v186, v199
	v_pk_mul_f32 v[186:187], v[224:225], v[186:187]
	v_pk_mul_f32 v[176:177], v[108:109], v[176:177]
	v_mul_f32_e32 v194, v106, v198
	v_mov_b32_e32 v195, v186
	v_mov_b32_e32 v197, v187
	v_pk_fma_f32 v[166:167], v[166:167], v[226:227], v[176:177]
	v_pk_fma_f32 v[172:173], v[172:173], v[228:229], v[178:179]
	v_pk_fma_f32 v[176:177], v[192:193], v[222:223], v[190:191]
	v_pk_add_f32 v[178:179], v[194:195], v[196:197]

;     __device__ __forceinline__ void operator()(const f32x4 (&acc)[2][2][4][2], const Unit& u, int wr, int wc, int fr, int fq) const {
;     ...
;                             if (fq < 2) {
;                                 const f32x4* cp = (const f32x4*)(csd + pos * 16);
;                                 const f32x4 c0 = cp[0], c1 = cp[1], s0 = cp[2], s1 = cp[3];
;                                 const float cs[8] = {c0[0], c0[1], c0[2], c0[3], c1[0], c1[1], c1[2], c1[3]};
;                                 const float sn[8] = {s0[0], s0[1], s0[2], s0[3], s1[0], s1[1], s1[2], s1[3]};
;                                 const float sg = fq == 0 ? -1.f : 1.f;
; #pragma unroll
;                                 for (int e = 0; e < 8; ++e) v[e] = v[e] * cs[e] + sg * pr[e] * sn[e];
.LBB0_471:
	s_cmp_lg_u32 s45, 1
	s_cbranch_scc0 .LBB0_476
	s_andn2_b64 vcc, exec, s[86:87]
	s_cbranch_vccnz .LBB0_477
	v_and_b32_e32 v160, 64, v210
	v_xor_b32_e32 v155, 16, v210
	v_add_u32_e32 v160, 64, v160
	v_cmp_lt_i32_e32 vcc, v155, v160
	v_mov_b32_e32 v191, v75
	v_mov_b32_e32 v190, v74
	v_cndmask_b32_e32 v155, v210, v155, vcc
	v_lshlrev_b32_e32 v155, 2, v155
	ds_bpermute_b32 v196, v155, v76
	ds_bpermute_b32 v197, v155, v77
	ds_bpermute_b32 v194, v155, v78
	ds_bpermute_b32 v195, v155, v79
	ds_bpermute_b32 v192, v155, v72
	ds_bpermute_b32 v193, v155, v73
	ds_bpermute_b32 v160, v155, v74
	ds_bpermute_b32 v155, v155, v75
	v_mov_b32_e32 v185, v73
	v_mov_b32_e32 v184, v72
	v_mov_b32_e32 v177, v79
	v_mov_b32_e32 v176, v78
	v_mov_b32_e32 v171, v77
	v_mov_b32_e32 v170, v76
	s_and_saveexec_b64 s[4:5], s[6:7]
	s_cbranch_execz .LBB0_475
	v_lshl_add_u32 v159, v159, 2, s98
	ds_read_b128 v[222:225], v159
	ds_read_b128 v[226:229], v159 offset:16
	ds_read_b128 v[230:233], v159 offset:48
	ds_read_b128 v[234:237], v159 offset:32
	s_waitcnt lgkmcnt(0)
	v_cndmask_b32_e64 v159, v160, -v160, s[10:11]
	v_cndmask_b32_e64 v176, v194, -v194, s[10:11]
	v_cndmask_b32_e64 v177, v195, -v195, s[10:11]
	v_cndmask_b32_e64 v191, v155, -v155, s[10:11]
	v_cndmask_b32_e64 v170, v196, -v196, s[10:11]
	v_cndmask_b32_e64 v171, v197, -v197, s[10:11]
	v_cndmask_b32_e64 v184, v192, -v192, s[10:11]
	v_cndmask_b32_e64 v185, v193, -v193, s[10:11]
	s_waitcnt lgkmcnt(0)
	v_pk_mul_f32 v[194:195], v[76:77], v[222:223]
	v_mov_b32_e32 v190, v229
	v_mul_f32_e32 v222, v159, v232
	v_mov_b32_e32 v232, v75
	v_pk_mul_f32 v[190:191], v[232:233], v[190:191]
	v_pk_mul_f32 v[192:193], v[78:79], v[224:225]
	v_pk_mul_f32 v[196:197], v[72:73], v[226:227]
	v_mul_f32_e32 v198, v74, v228
	v_mov_b32_e32 v199, v190
	v_mov_b32_e32 v223, v191
	v_pk_fma_f32 v[170:171], v[170:171], v[234:235], v[194:195]
	v_pk_fma_f32 v[176:177], v[176:177], v[236:237], v[192:193]
	v_pk_fma_f32 v[184:185], v[184:185], v[230:231], v[196:197]
	v_pk_add_f32 v[190:191], v[198:199], v[222:223]

;     __device__ __forceinline__ void operator()(const f32x4 (&acc)[2][2][4][2], const Unit& u, int wr, int wc, int fr, int fq) const {
;     ...
;                             if (fq < 2) {
;                                 const f32x4* cp = (const f32x4*)(csd + pos * 16);
;                                 const f32x4 c0 = cp[0], c1 = cp[1], s0 = cp[2], s1 = cp[3];
;                                 const float cs[8] = {c0[0], c0[1], c0[2], c0[3], c1[0], c1[1], c1[2], c1[3]};
;                                 const float sn[8] = {s0[0], s0[1], s0[2], s0[3], s1[0], s1[1], s1[2], s1[3]};
;                                 const float sg = fq == 0 ? -1.f : 1.f;
; #pragma unroll
;                                 for (int e = 0; e < 8; ++e) v[e] = v[e] * cs[e] + sg * pr[e] * sn[e];
.LBB0_491:
	s_andn2_b64 vcc, exec, s[4:5]
	v_lshlrev_b32_e32 v159, 4, v159
	s_cbranch_vccnz .LBB0_501
	s_cmp_lg_u32 s45, 1
	s_cbranch_scc0 .LBB0_497
	s_andn2_b64 vcc, exec, s[86:87]
	s_cbranch_vccnz .LBB0_498
	v_and_b32_e32 v164, 64, v210
	v_xor_b32_e32 v160, 16, v210
	v_add_u32_e32 v164, 64, v164
	v_cmp_lt_i32_e32 vcc, v160, v164
	v_mov_b32_e32 v181, v99
	v_mov_b32_e32 v180, v98
	v_cndmask_b32_e32 v160, v210, v160, vcc
	v_lshlrev_b32_e32 v160, 2, v160
	ds_bpermute_b32 v193, v160, v100
	ds_bpermute_b32 v194, v160, v101
	ds_bpermute_b32 v189, v160, v102
	ds_bpermute_b32 v192, v160, v103
	ds_bpermute_b32 v183, v160, v96
	ds_bpermute_b32 v188, v160, v97
	ds_bpermute_b32 v182, v160, v98
	ds_bpermute_b32 v160, v160, v99
	v_mov_b32_e32 v175, v97
	v_mov_b32_e32 v174, v96
	v_mov_b32_e32 v169, v103
	v_mov_b32_e32 v168, v102
	v_mov_b32_e32 v165, v101
	v_mov_b32_e32 v164, v100
	s_and_saveexec_b64 s[4:5], s[6:7]
	s_cbranch_execz .LBB0_496
	v_lshl_add_u32 v164, v159, 2, s98
	ds_read_b128 v[196:199], v164
	ds_read_b128 v[222:225], v164 offset:16
	ds_read_b128 v[226:229], v164 offset:48
	ds_read_b128 v[230:233], v164 offset:32
	s_waitcnt lgkmcnt(0)
	v_cndmask_b32_e64 v180, v182, -v182, s[10:11]
	v_cndmask_b32_e64 v168, v189, -v189, s[10:11]
	v_cndmask_b32_e64 v175, v188, -v188, s[10:11]
	v_cndmask_b32_e64 v181, v160, -v160, s[10:11]
	v_cndmask_b32_e64 v164, v193, -v193, s[10:11]
	v_cndmask_b32_e64 v165, v194, -v194, s[10:11]
	v_cndmask_b32_e64 v169, v192, -v192, s[10:11]
	v_cndmask_b32_e64 v174, v183, -v183, s[10:11]
	s_waitcnt lgkmcnt(0)
	v_pk_mul_f32 v[188:189], v[100:101], v[196:197]
	v_pk_mul_f32 v[182:183], v[102:103], v[198:199]
	v_mul_f32_e32 v196, v180, v228
	v_mov_b32_e32 v228, v99
	v_mov_b32_e32 v180, v225
	v_pk_mul_f32 v[180:181], v[228:229], v[180:181]
	v_pk_mul_f32 v[192:193], v[96:97], v[222:223]
	v_mul_f32_e32 v194, v98, v224
	v_mov_b32_e32 v195, v180
	v_mov_b32_e32 v197, v181
	v_pk_fma_f32 v[164:165], v[164:165], v[230:231], v[188:189]
	v_pk_fma_f32 v[168:169], v[168:169], v[232:233], v[182:183]
	v_pk_fma_f32 v[174:175], v[174:175], v[226:227], v[192:193]
	v_pk_add_f32 v[180:181], v[194:195], v[196:197]

;     __device__ __forceinline__ void operator()(const f32x4 (&acc)[2][2][4][2], const Unit& u, int wr, int wc, int fr, int fq) const {
;     ...
;                             if (fq < 2) {
;                                 const f32x4* cp = (const f32x4*)(csd + pos * 16);
;                                 const f32x4 c0 = cp[0], c1 = cp[1], s0 = cp[2], s1 = cp[3];
;                                 const float cs[8] = {c0[0], c0[1], c0[2], c0[3], c1[0], c1[1], c1[2], c1[3]};
;                                 const float sn[8] = {s0[0], s0[1], s0[2], s0[3], s1[0], s1[1], s1[2], s1[3]};
;                                 const float sg = fq == 0 ? -1.f : 1.f;
; #pragma unroll
;                                 for (int e = 0; e < 8; ++e) v[e] = v[e] * cs[e] + sg * pr[e] * sn[e];
.LBB0_517:
	s_cmp_lg_u32 s45, 1
	s_cbranch_scc0 .LBB0_522
	s_andn2_b64 vcc, exec, s[86:87]
	s_cbranch_vccnz .LBB0_523
	v_and_b32_e32 v160, 64, v210
	v_xor_b32_e32 v155, 16, v210
	v_add_u32_e32 v160, 64, v160
	v_cmp_lt_i32_e32 vcc, v155, v160
	v_mov_b32_e32 v187, v67
	v_mov_b32_e32 v186, v66
	v_cndmask_b32_e32 v155, v210, v155, vcc
	v_lshlrev_b32_e32 v155, 2, v155
	ds_bpermute_b32 v196, v155, v68
	ds_bpermute_b32 v197, v155, v69
	ds_bpermute_b32 v194, v155, v70
	ds_bpermute_b32 v195, v155, v71
	ds_bpermute_b32 v192, v155, v64
	ds_bpermute_b32 v193, v155, v65
	ds_bpermute_b32 v160, v155, v66
	ds_bpermute_b32 v155, v155, v67
	v_mov_b32_e32 v183, v65
	v_mov_b32_e32 v182, v64
	v_mov_b32_e32 v179, v71
	v_mov_b32_e32 v178, v70
	v_mov_b32_e32 v169, v69
	v_mov_b32_e32 v168, v68
	s_and_saveexec_b64 s[4:5], s[6:7]
	s_cbranch_execz .LBB0_521
	v_lshl_add_u32 v159, v159, 2, s98
	ds_read_b128 v[222:225], v159
	ds_read_b128 v[226:229], v159 offset:16
	ds_read_b128 v[230:233], v159 offset:48
	ds_read_b128 v[234:237], v159 offset:32
	s_waitcnt lgkmcnt(0)
	v_cndmask_b32_e64 v159, v160, -v160, s[10:11]
	v_cndmask_b32_e64 v178, v194, -v194, s[10:11]
	v_cndmask_b32_e64 v179, v195, -v195, s[10:11]
	v_cndmask_b32_e64 v187, v155, -v155, s[10:11]
	v_cndmask_b32_e64 v168, v196, -v196, s[10:11]
	v_cndmask_b32_e64 v169, v197, -v197, s[10:11]
	v_cndmask_b32_e64 v182, v192, -v192, s[10:11]
	v_cndmask_b32_e64 v183, v193, -v193, s[10:11]
	s_waitcnt lgkmcnt(0)
	v_pk_mul_f32 v[194:195], v[68:69], v[222:223]
	v_mov_b32_e32 v186, v229
	v_mul_f32_e32 v222, v159, v232
	v_mov_b32_e32 v232, v67
	v_pk_mul_f32 v[186:187], v[232:233], v[186:187]
	v_pk_mul_f32 v[192:193], v[70:71], v[224:225]
	v_pk_mul_f32 v[196:197], v[64:65], v[226:227]
	v_mul_f32_e32 v198, v66, v228
	v_mov_b32_e32 v199, v186
	v_mov_b32_e32 v223, v187
	v_pk_fma_f32 v[168:169], v[168:169], v[234:235], v[194:195]
	v_pk_fma_f32 v[178:179], v[178:179], v[236:237], v[192:193]
	v_pk_fma_f32 v[182:183], v[182:183], v[230:231], v[196:197]
	v_pk_add_f32 v[186:187], v[198:199], v[222:223]

;     __device__ __forceinline__ void operator()(const f32x4 (&acc)[2][2][4][2], const Unit& u, int wr, int wc, int fr, int fq) const {
;     ...
;                             if (fq < 2) {
;                                 const f32x4* cp = (const f32x4*)(csd + pos * 16);
;                                 const f32x4 c0 = cp[0], c1 = cp[1], s0 = cp[2], s1 = cp[3];
;                                 const float cs[8] = {c0[0], c0[1], c0[2], c0[3], c1[0], c1[1], c1[2], c1[3]};
;                                 const float sn[8] = {s0[0], s0[1], s0[2], s0[3], s1[0], s1[1], s1[2], s1[3]};
;                                 const float sg = fq == 0 ? -1.f : 1.f;
; #pragma unroll
;                                 for (int e = 0; e < 8; ++e) v[e] = v[e] * cs[e] + sg * pr[e] * sn[e];
.LBB0_537:
	s_andn2_b64 vcc, exec, s[4:5]
	v_lshlrev_b32_e32 v159, 4, v159
	s_cbranch_vccnz .LBB0_547
	s_cmp_lg_u32 s45, 1
	s_cbranch_scc0 .LBB0_543
	s_andn2_b64 vcc, exec, s[86:87]
	s_cbranch_vccnz .LBB0_544
	v_and_b32_e32 v166, 64, v210
	v_xor_b32_e32 v160, 16, v210
	v_add_u32_e32 v166, 64, v166
	v_cmp_lt_i32_e32 vcc, v160, v166
	v_mov_b32_e32 v183, v59
	v_mov_b32_e32 v182, v58
	v_cndmask_b32_e32 v160, v210, v160, vcc
	v_lshlrev_b32_e32 v160, 2, v160
	ds_bpermute_b32 v194, v160, v60
	ds_bpermute_b32 v195, v160, v61
	ds_bpermute_b32 v190, v160, v62
	ds_bpermute_b32 v191, v160, v63
	ds_bpermute_b32 v184, v160, v56
	ds_bpermute_b32 v185, v160, v57
	ds_bpermute_b32 v171, v160, v58
	ds_bpermute_b32 v160, v160, v59
	v_mov_b32_e32 v177, v57
	v_mov_b32_e32 v176, v56
	v_mov_b32_e32 v173, v63
	v_mov_b32_e32 v172, v62
	v_mov_b32_e32 v167, v61
	v_mov_b32_e32 v166, v60
	s_and_saveexec_b64 s[4:5], s[6:7]
	s_cbranch_execz .LBB0_542
	v_lshl_add_u32 v166, v159, 2, s98
	ds_read_b128 v[196:199], v166
	ds_read_b128 v[222:225], v166 offset:16
	ds_read_b128 v[226:229], v166 offset:48
	ds_read_b128 v[230:233], v166 offset:32
	s_waitcnt lgkmcnt(0)
	v_cndmask_b32_e64 v171, v171, -v171, s[10:11]
	v_cndmask_b32_e64 v176, v184, -v184, s[10:11]
	v_cndmask_b32_e64 v177, v185, -v185, s[10:11]
	v_cndmask_b32_e64 v183, v160, -v160, s[10:11]
	v_cndmask_b32_e64 v166, v194, -v194, s[10:11]
	v_cndmask_b32_e64 v167, v195, -v195, s[10:11]
	v_cndmask_b32_e64 v172, v190, -v190, s[10:11]
	v_cndmask_b32_e64 v173, v191, -v191, s[10:11]
	s_waitcnt lgkmcnt(0)
	v_pk_mul_f32 v[184:185], v[62:63], v[198:199]
	v_mov_b32_e32 v182, v225
	v_mul_f32_e32 v198, v171, v228
	v_mov_b32_e32 v228, v59
	v_pk_mul_f32 v[182:183], v[228:229], v[182:183]
	v_pk_mul_f32 v[190:191], v[60:61], v[196:197]
	v_pk_mul_f32 v[194:195], v[56:57], v[222:223]
	v_mul_f32_e32 v196, v58, v224
	v_mov_b32_e32 v197, v182
	v_mov_b32_e32 v199, v183
	v_pk_fma_f32 v[166:167], v[166:167], v[230:231], v[190:191]
	v_pk_fma_f32 v[172:173], v[172:173], v[232:233], v[184:185]
	v_pk_fma_f32 v[176:177], v[176:177], v[226:227], v[194:195]
	v_pk_add_f32 v[182:183], v[196:197], v[198:199]

;     __device__ __forceinline__ void operator()(const f32x4 (&acc)[2][2][4][2], const Unit& u, int wr, int wc, int fr, int fq) const {
;     ...
;                             if (fq < 2) {
;                                 const f32x4* cp = (const f32x4*)(csd + pos * 16);
;                                 const f32x4 c0 = cp[0], c1 = cp[1], s0 = cp[2], s1 = cp[3];
;                                 const float cs[8] = {c0[0], c0[1], c0[2], c0[3], c1[0], c1[1], c1[2], c1[3]};
;                                 const float sn[8] = {s0[0], s0[1], s0[2], s0[3], s1[0], s1[1], s1[2], s1[3]};
;                                 const float sg = fq == 0 ? -1.f : 1.f;
; #pragma unroll
;                                 for (int e = 0; e < 8; ++e) v[e] = v[e] * cs[e] + sg * pr[e] * sn[e];
.LBB0_563:
	s_cmp_lg_u32 s45, 1
	s_cbranch_scc0 .LBB0_568
	s_andn2_b64 vcc, exec, s[86:87]
	s_cbranch_vccnz .LBB0_569
	v_and_b32_e32 v160, 64, v210
	v_xor_b32_e32 v155, 16, v210
	v_add_u32_e32 v160, 64, v160
	v_cmp_lt_i32_e32 vcc, v155, v160
	v_mov_b32_e32 v189, v27
	v_mov_b32_e32 v188, v26
	v_cndmask_b32_e32 v155, v210, v155, vcc
	v_lshlrev_b32_e32 v155, 2, v155
	ds_bpermute_b32 v196, v155, v28
	ds_bpermute_b32 v197, v155, v29
	ds_bpermute_b32 v194, v155, v30
	ds_bpermute_b32 v195, v155, v31
	ds_bpermute_b32 v190, v155, v24
	ds_bpermute_b32 v191, v155, v25
	ds_bpermute_b32 v160, v155, v26
	ds_bpermute_b32 v155, v155, v27
	v_mov_b32_e32 v181, v25
	v_mov_b32_e32 v180, v24
	v_mov_b32_e32 v177, v31
	v_mov_b32_e32 v176, v30
	v_mov_b32_e32 v171, v29
	v_mov_b32_e32 v170, v28
	s_and_saveexec_b64 s[4:5], s[6:7]
	s_cbranch_execz .LBB0_567
	v_lshl_add_u32 v159, v159, 2, s98
	ds_read_b128 v[222:225], v159
	ds_read_b128 v[226:229], v159 offset:16
	ds_read_b128 v[230:233], v159 offset:48
	ds_read_b128 v[234:237], v159 offset:32
	s_waitcnt lgkmcnt(0)
	v_cndmask_b32_e64 v159, v160, -v160, s[10:11]
	v_cndmask_b32_e64 v176, v194, -v194, s[10:11]
	v_cndmask_b32_e64 v177, v195, -v195, s[10:11]
	v_cndmask_b32_e64 v189, v155, -v155, s[10:11]
	v_cndmask_b32_e64 v170, v196, -v196, s[10:11]
	v_cndmask_b32_e64 v171, v197, -v197, s[10:11]
	v_cndmask_b32_e64 v180, v190, -v190, s[10:11]
	v_cndmask_b32_e64 v181, v191, -v191, s[10:11]
	s_waitcnt lgkmcnt(0)
	v_pk_mul_f32 v[194:195], v[28:29], v[222:223]
	v_mov_b32_e32 v188, v229
	v_mul_f32_e32 v222, v159, v232
	v_mov_b32_e32 v232, v27
	v_pk_mul_f32 v[188:189], v[232:233], v[188:189]
	v_pk_mul_f32 v[190:191], v[30:31], v[224:225]
	v_pk_mul_f32 v[196:197], v[24:25], v[226:227]
	v_mul_f32_e32 v198, v26, v228
	v_mov_b32_e32 v199, v188
	v_mov_b32_e32 v223, v189
	v_pk_fma_f32 v[170:171], v[170:171], v[234:235], v[194:195]
	v_pk_fma_f32 v[176:177], v[176:177], v[236:237], v[190:191]
	v_pk_fma_f32 v[180:181], v[180:181], v[230:231], v[196:197]
	v_pk_add_f32 v[188:189], v[198:199], v[222:223]

;     __device__ __forceinline__ void operator()(const f32x4 (&acc)[2][2][4][2], const Unit& u, int wr, int wc, int fr, int fq) const {
;     ...
;                             if (fq < 2) {
;                                 const f32x4* cp = (const f32x4*)(csd + pos * 16);
;                                 const f32x4 c0 = cp[0], c1 = cp[1], s0 = cp[2], s1 = cp[3];
;                                 const float cs[8] = {c0[0], c0[1], c0[2], c0[3], c1[0], c1[1], c1[2], c1[3]};
;                                 const float sn[8] = {s0[0], s0[1], s0[2], s0[3], s1[0], s1[1], s1[2], s1[3]};
;                                 const float sg = fq == 0 ? -1.f : 1.f;
; #pragma unroll
;                                 for (int e = 0; e < 8; ++e) v[e] = v[e] * cs[e] + sg * pr[e] * sn[e];
.LBB0_583:
	s_andn2_b64 vcc, exec, s[4:5]
	v_lshlrev_b32_e32 v159, 4, v159
	s_cbranch_vccnz .LBB0_593
	s_cmp_lg_u32 s45, 1
	s_cbranch_scc0 .LBB0_589
	s_andn2_b64 vcc, exec, s[86:87]
	s_cbranch_vccnz .LBB0_590
	v_and_b32_e32 v164, 64, v210
	v_xor_b32_e32 v160, 16, v210
	v_add_u32_e32 v164, 64, v164
	v_cmp_lt_i32_e32 vcc, v160, v164
	v_mov_b32_e32 v187, v51
	v_mov_b32_e32 v186, v50
	v_cndmask_b32_e32 v160, v210, v160, vcc
	v_lshlrev_b32_e32 v160, 2, v160
	ds_bpermute_b32 v194, v160, v52
	ds_bpermute_b32 v195, v160, v53
	ds_bpermute_b32 v192, v160, v54
	ds_bpermute_b32 v193, v160, v55
	ds_bpermute_b32 v190, v160, v48
	ds_bpermute_b32 v191, v160, v49
	ds_bpermute_b32 v169, v160, v50
	ds_bpermute_b32 v160, v160, v51
	v_mov_b32_e32 v179, v49
	v_mov_b32_e32 v178, v48
	v_mov_b32_e32 v175, v55
	v_mov_b32_e32 v174, v54
	v_mov_b32_e32 v165, v53
	v_mov_b32_e32 v164, v52
	s_and_saveexec_b64 s[4:5], s[6:7]
	s_cbranch_execz .LBB0_588
	v_lshl_add_u32 v164, v159, 2, s98
	ds_read_b128 v[196:199], v164
	ds_read_b128 v[222:225], v164 offset:16
	ds_read_b128 v[226:229], v164 offset:48
	ds_read_b128 v[230:233], v164 offset:32
	s_waitcnt lgkmcnt(0)
	v_cndmask_b32_e64 v169, v169, -v169, s[10:11]
	v_cndmask_b32_e64 v178, v190, -v190, s[10:11]
	v_cndmask_b32_e64 v179, v191, -v191, s[10:11]
	v_cndmask_b32_e64 v187, v160, -v160, s[10:11]
	v_cndmask_b32_e64 v164, v194, -v194, s[10:11]
	v_cndmask_b32_e64 v165, v195, -v195, s[10:11]
	v_cndmask_b32_e64 v174, v192, -v192, s[10:11]
	v_cndmask_b32_e64 v175, v193, -v193, s[10:11]
	s_waitcnt lgkmcnt(0)
	v_pk_mul_f32 v[190:191], v[54:55], v[198:199]
	v_mov_b32_e32 v186, v225
	v_mul_f32_e32 v198, v169, v228
	v_mov_b32_e32 v228, v51
	v_pk_mul_f32 v[186:187], v[228:229], v[186:187]
	v_pk_mul_f32 v[192:193], v[52:53], v[196:197]
	v_pk_mul_f32 v[194:195], v[48:49], v[222:223]
	v_mul_f32_e32 v196, v50, v224
	v_mov_b32_e32 v197, v186
	v_mov_b32_e32 v199, v187
	v_pk_fma_f32 v[164:165], v[164:165], v[230:231], v[192:193]
	v_pk_fma_f32 v[174:175], v[174:175], v[232:233], v[190:191]
	v_pk_fma_f32 v[178:179], v[178:179], v[226:227], v[194:195]
	v_pk_add_f32 v[186:187], v[196:197], v[198:199]

;     __device__ __forceinline__ void operator()(const f32x4 (&acc)[2][2][4][2], const Unit& u, int wr, int wc, int fr, int fq) const {
;     ...
;                             if (fq < 2) {
;                                 const f32x4* cp = (const f32x4*)(csd + pos * 16);
;                                 const f32x4 c0 = cp[0], c1 = cp[1], s0 = cp[2], s1 = cp[3];
;                                 const float cs[8] = {c0[0], c0[1], c0[2], c0[3], c1[0], c1[1], c1[2], c1[3]};
;                                 const float sn[8] = {s0[0], s0[1], s0[2], s0[3], s1[0], s1[1], s1[2], s1[3]};
;                                 const float sg = fq == 0 ? -1.f : 1.f;
; #pragma unroll
;                                 for (int e = 0; e < 8; ++e) v[e] = v[e] * cs[e] + sg * pr[e] * sn[e];
.LBB0_609:
	s_cmp_lg_u32 s45, 1
	s_cbranch_scc0 .LBB0_614
	s_andn2_b64 vcc, exec, s[86:87]
	s_cbranch_vccnz .LBB0_615
	v_and_b32_e32 v160, 64, v210
	v_xor_b32_e32 v155, 16, v210
	v_add_u32_e32 v160, 64, v160
	v_cmp_lt_i32_e32 vcc, v155, v160
	v_mov_b32_e32 v185, v19
	v_mov_b32_e32 v184, v18
	v_cndmask_b32_e32 v155, v210, v155, vcc
	v_lshlrev_b32_e32 v155, 2, v155
	ds_bpermute_b32 v196, v155, v20
	ds_bpermute_b32 v197, v155, v21
	ds_bpermute_b32 v194, v155, v22
	ds_bpermute_b32 v195, v155, v23
	ds_bpermute_b32 v192, v155, v16
	ds_bpermute_b32 v193, v155, v17
	ds_bpermute_b32 v160, v155, v18
	ds_bpermute_b32 v155, v155, v19
	v_mov_b32_e32 v183, v17
	v_mov_b32_e32 v182, v16
	v_mov_b32_e32 v173, v23
	v_mov_b32_e32 v172, v22
	v_mov_b32_e32 v169, v21
	v_mov_b32_e32 v168, v20
	s_and_saveexec_b64 s[4:5], s[6:7]
	s_cbranch_execz .LBB0_613
	v_lshl_add_u32 v159, v159, 2, s98
	ds_read_b128 v[182:185], v159
	ds_read_b128 v[222:225], v159 offset:16
	ds_read_b128 v[226:229], v159 offset:48
	ds_read_b128 v[230:233], v159 offset:32
	s_waitcnt lgkmcnt(0)
	v_cndmask_b32_e64 v159, v160, -v160, s[10:11]
	v_cndmask_b32_e64 v168, v196, -v196, s[10:11]
	v_cndmask_b32_e64 v169, v197, -v197, s[10:11]
	v_cndmask_b32_e64 v172, v194, -v194, s[10:11]
	v_cndmask_b32_e64 v173, v195, -v195, s[10:11]
	v_cndmask_b32_e64 v195, v155, -v155, s[10:11]
	v_cndmask_b32_e64 v192, v192, -v192, s[10:11]
	v_cndmask_b32_e64 v193, v193, -v193, s[10:11]
	s_waitcnt lgkmcnt(0)
	v_pk_mul_f32 v[184:185], v[22:23], v[184:185]
	v_pk_mul_f32 v[196:197], v[16:17], v[222:223]
	v_mul_f32_e32 v222, v159, v228
	v_mov_b32_e32 v228, v19
	v_mov_b32_e32 v194, v225
	v_pk_mul_f32 v[194:195], v[228:229], v[194:195]
	v_pk_mul_f32 v[182:183], v[20:21], v[182:183]
	v_mul_f32_e32 v198, v18, v224
	v_mov_b32_e32 v199, v194
	v_mov_b32_e32 v223, v195
	v_pk_fma_f32 v[168:169], v[168:169], v[230:231], v[182:183]
	v_pk_fma_f32 v[172:173], v[172:173], v[232:233], v[184:185]
	v_pk_fma_f32 v[182:183], v[192:193], v[226:227], v[196:197]
	v_pk_add_f32 v[184:185], v[198:199], v[222:223]

;     __device__ __forceinline__ void operator()(const f32x4 (&acc)[2][2][4][2], const Unit& u, int wr, int wc, int fr, int fq) const {
;     ...
;                             if (fq < 2) {
;                                 const f32x4* cp = (const f32x4*)(csd + pos * 16);
;                                 const f32x4 c0 = cp[0], c1 = cp[1], s0 = cp[2], s1 = cp[3];
;                                 const float cs[8] = {c0[0], c0[1], c0[2], c0[3], c1[0], c1[1], c1[2], c1[3]};
;                                 const float sn[8] = {s0[0], s0[1], s0[2], s0[3], s1[0], s1[1], s1[2], s1[3]};
;                                 const float sg = fq == 0 ? -1.f : 1.f;
; #pragma unroll
;                                 for (int e = 0; e < 8; ++e) v[e] = v[e] * cs[e] + sg * pr[e] * sn[e];
.LBB0_629:
	s_andn2_b64 vcc, exec, s[4:5]
	v_lshlrev_b32_e32 v159, 4, v159
	s_cbranch_vccnz .LBB0_639
	s_cmp_lg_u32 s45, 1
	s_cbranch_scc0 .LBB0_635
	s_andn2_b64 vcc, exec, s[86:87]
	s_cbranch_vccnz .LBB0_636
	v_and_b32_e32 v166, 64, v210
	v_xor_b32_e32 v160, 16, v210
	v_add_u32_e32 v166, 64, v166
	v_cmp_lt_i32_e32 vcc, v160, v166
	v_mov_b32_e32 v181, v43
	v_mov_b32_e32 v180, v42
	v_cndmask_b32_e32 v160, v210, v160, vcc
	v_lshlrev_b32_e32 v160, 2, v160
	ds_bpermute_b32 v194, v160, v44
	ds_bpermute_b32 v195, v160, v45
	ds_bpermute_b32 v192, v160, v46
	ds_bpermute_b32 v193, v160, v47
	ds_bpermute_b32 v189, v160, v40
	ds_bpermute_b32 v191, v160, v41
	ds_bpermute_b32 v188, v160, v42
	ds_bpermute_b32 v160, v160, v43
	v_mov_b32_e32 v177, v41
	v_mov_b32_e32 v176, v40
	v_mov_b32_e32 v171, v47
	v_mov_b32_e32 v170, v46
	v_mov_b32_e32 v167, v45
	v_mov_b32_e32 v166, v44
	s_and_saveexec_b64 s[4:5], s[6:7]
	s_cbranch_execz .LBB0_634
	v_lshl_add_u32 v166, v159, 2, s98
	ds_read_b128 v[196:199], v166
	ds_read_b128 v[222:225], v166 offset:16
	ds_read_b128 v[226:229], v166 offset:48
	ds_read_b128 v[230:233], v166 offset:32
	s_waitcnt lgkmcnt(0)
	v_cndmask_b32_e64 v180, v188, -v188, s[10:11]
	v_cndmask_b32_e64 v176, v189, -v189, s[10:11]
	v_cndmask_b32_e64 v181, v160, -v160, s[10:11]
	v_cndmask_b32_e64 v166, v194, -v194, s[10:11]
	v_cndmask_b32_e64 v167, v195, -v195, s[10:11]
	v_cndmask_b32_e64 v170, v192, -v192, s[10:11]
	v_cndmask_b32_e64 v171, v193, -v193, s[10:11]
	v_cndmask_b32_e64 v177, v191, -v191, s[10:11]
	s_waitcnt lgkmcnt(0)
	v_pk_mul_f32 v[188:189], v[46:47], v[198:199]
	v_pk_mul_f32 v[192:193], v[44:45], v[196:197]
	v_mul_f32_e32 v198, v180, v228
	v_mov_b32_e32 v228, v43
	v_mov_b32_e32 v180, v225
	v_pk_mul_f32 v[180:181], v[228:229], v[180:181]
	v_pk_mul_f32 v[194:195], v[40:41], v[222:223]
	v_mul_f32_e32 v196, v42, v224
	v_mov_b32_e32 v197, v180
	v_mov_b32_e32 v199, v181
	v_pk_fma_f32 v[166:167], v[166:167], v[230:231], v[192:193]
	v_pk_fma_f32 v[170:171], v[170:171], v[232:233], v[188:189]
	v_pk_fma_f32 v[176:177], v[176:177], v[226:227], v[194:195]
	v_pk_add_f32 v[180:181], v[196:197], v[198:199]

;     __device__ __forceinline__ void operator()(const f32x4 (&acc)[2][2][4][2], const Unit& u, int wr, int wc, int fr, int fq) const {
;     ...
;                             if (fq < 2) {
;                                 const f32x4* cp = (const f32x4*)(csd + pos * 16);
;                                 const f32x4 c0 = cp[0], c1 = cp[1], s0 = cp[2], s1 = cp[3];
;                                 const float cs[8] = {c0[0], c0[1], c0[2], c0[3], c1[0], c1[1], c1[2], c1[3]};
;                                 const float sn[8] = {s0[0], s0[1], s0[2], s0[3], s1[0], s1[1], s1[2], s1[3]};
;                                 const float sg = fq == 0 ? -1.f : 1.f;
; #pragma unroll
;                                 for (int e = 0; e < 8; ++e) v[e] = v[e] * cs[e] + sg * pr[e] * sn[e];
.LBB0_655:
	s_cmp_lg_u32 s45, 1
	s_cbranch_scc0 .LBB0_660
	s_andn2_b64 vcc, exec, s[86:87]
	s_cbranch_vccnz .LBB0_661
	v_and_b32_e32 v160, 64, v210
	v_xor_b32_e32 v155, 16, v210
	v_add_u32_e32 v160, 64, v160
	v_cmp_lt_i32_e32 vcc, v155, v160
	v_mov_b32_e32 v187, v11
	v_mov_b32_e32 v186, v10
	v_cndmask_b32_e32 v155, v210, v155, vcc
	v_lshlrev_b32_e32 v155, 2, v155
	ds_bpermute_b32 v196, v155, v12
	ds_bpermute_b32 v197, v155, v13
	ds_bpermute_b32 v194, v155, v14
	ds_bpermute_b32 v195, v155, v15
	ds_bpermute_b32 v192, v155, v8
	ds_bpermute_b32 v193, v155, v9
	ds_bpermute_b32 v160, v155, v10
	ds_bpermute_b32 v155, v155, v11
	v_mov_b32_e32 v179, v9
	v_mov_b32_e32 v178, v8
	v_mov_b32_e32 v175, v15
	v_mov_b32_e32 v174, v14
	v_mov_b32_e32 v165, v13
	v_mov_b32_e32 v164, v12
	s_and_saveexec_b64 s[4:5], s[6:7]
	s_cbranch_execz .LBB0_659
	v_lshl_add_u32 v159, v159, 2, s98
	ds_read_b128 v[222:225], v159
	ds_read_b128 v[226:229], v159 offset:16
	ds_read_b128 v[230:233], v159 offset:48
	ds_read_b128 v[234:237], v159 offset:32
	s_waitcnt lgkmcnt(0)
	v_cndmask_b32_e64 v159, v160, -v160, s[10:11]
	v_cndmask_b32_e64 v174, v194, -v194, s[10:11]
	v_cndmask_b32_e64 v175, v195, -v195, s[10:11]
	v_cndmask_b32_e64 v187, v155, -v155, s[10:11]
	v_cndmask_b32_e64 v164, v196, -v196, s[10:11]
	v_cndmask_b32_e64 v165, v197, -v197, s[10:11]
	v_cndmask_b32_e64 v178, v192, -v192, s[10:11]
	v_cndmask_b32_e64 v179, v193, -v193, s[10:11]
	s_waitcnt lgkmcnt(0)
	v_pk_mul_f32 v[194:195], v[12:13], v[222:223]
	v_mov_b32_e32 v186, v229
	v_mul_f32_e32 v222, v159, v232
	v_mov_b32_e32 v232, v11
	v_pk_mul_f32 v[186:187], v[232:233], v[186:187]
	v_pk_mul_f32 v[192:193], v[14:15], v[224:225]
	v_pk_mul_f32 v[196:197], v[8:9], v[226:227]
	v_mul_f32_e32 v198, v10, v228
	v_mov_b32_e32 v199, v186
	v_mov_b32_e32 v223, v187
	v_pk_fma_f32 v[164:165], v[164:165], v[234:235], v[194:195]
	v_pk_fma_f32 v[174:175], v[174:175], v[236:237], v[192:193]
	v_pk_fma_f32 v[178:179], v[178:179], v[230:231], v[196:197]
	v_pk_add_f32 v[186:187], v[198:199], v[222:223]

;     __device__ __forceinline__ void operator()(const f32x4 (&acc)[2][2][4][2], const Unit& u, int wr, int wc, int fr, int fq) const {
;     ...
;                             if (fq < 2) {
;                                 const f32x4* cp = (const f32x4*)(csd + pos * 16);
;                                 const f32x4 c0 = cp[0], c1 = cp[1], s0 = cp[2], s1 = cp[3];
;                                 const float cs[8] = {c0[0], c0[1], c0[2], c0[3], c1[0], c1[1], c1[2], c1[3]};
;                                 const float sn[8] = {s0[0], s0[1], s0[2], s0[3], s1[0], s1[1], s1[2], s1[3]};
;                                 const float sg = fq == 0 ? -1.f : 1.f;
; #pragma unroll
;                                 for (int e = 0; e < 8; ++e) v[e] = v[e] * cs[e] + sg * pr[e] * sn[e];
.LBB0_675:
	s_andn2_b64 vcc, exec, s[4:5]
	v_lshlrev_b32_e32 v196, 4, v185
	s_cbranch_vccnz .LBB0_685
	s_cmp_lg_u32 s45, 1
	s_cbranch_scc0 .LBB0_681
	s_andn2_b64 vcc, exec, s[86:87]
	s_cbranch_vccnz .LBB0_682
	v_and_b32_e32 v159, 64, v210
	v_xor_b32_e32 v158, 16, v210
	v_add_u32_e32 v159, 64, v159
	v_cmp_lt_i32_e32 vcc, v158, v159
	v_mov_b32_e32 v183, v35
	v_mov_b32_e32 v182, v34
	v_cndmask_b32_e32 v158, v210, v158, vcc
	v_lshlrev_b32_e32 v158, 2, v158
	ds_bpermute_b32 v192, v158, v36
	ds_bpermute_b32 v193, v158, v37
	ds_bpermute_b32 v190, v158, v38
	ds_bpermute_b32 v191, v158, v39
	ds_bpermute_b32 v188, v158, v32
	ds_bpermute_b32 v189, v158, v33
	ds_bpermute_b32 v185, v158, v34
	ds_bpermute_b32 v160, v158, v35
	v_mov_b32_e32 v173, v33
	v_mov_b32_e32 v172, v32
	v_mov_b32_e32 v169, v39
	v_mov_b32_e32 v168, v38
	v_mov_b32_e32 v159, v37
	v_mov_b32_e32 v158, v36
	s_and_saveexec_b64 s[4:5], s[6:7]
	s_cbranch_execz .LBB0_680
	v_lshl_add_u32 v158, v196, 2, s98
	ds_read_b128 v[222:225], v158
	ds_read_b128 v[226:229], v158 offset:16
	ds_read_b128 v[230:233], v158 offset:48
	ds_read_b128 v[234:237], v158 offset:32
	s_waitcnt lgkmcnt(0)
	v_cndmask_b32_e64 v182, v185, -v185, s[10:11]
	v_cndmask_b32_e64 v183, v160, -v160, s[10:11]
	v_cndmask_b32_e64 v158, v192, -v192, s[10:11]
	v_cndmask_b32_e64 v159, v193, -v193, s[10:11]
	v_cndmask_b32_e64 v168, v190, -v190, s[10:11]
	v_cndmask_b32_e64 v169, v191, -v191, s[10:11]
	v_cndmask_b32_e64 v172, v188, -v188, s[10:11]
	v_cndmask_b32_e64 v173, v189, -v189, s[10:11]
	s_waitcnt lgkmcnt(0)
	v_pk_mul_f32 v[188:189], v[38:39], v[224:225]
	v_pk_mul_f32 v[190:191], v[36:37], v[222:223]
	v_mul_f32_e32 v198, v182, v232
	v_mov_b32_e32 v232, v35
	v_mov_b32_e32 v182, v229
	v_pk_mul_f32 v[182:183], v[232:233], v[182:183]
	v_pk_mul_f32 v[192:193], v[32:33], v[226:227]
	v_mul_f32_e32 v194, v34, v228
	v_mov_b32_e32 v195, v182
	v_mov_b32_e32 v199, v183
	v_pk_fma_f32 v[158:159], v[158:159], v[234:235], v[190:191]
	v_pk_fma_f32 v[168:169], v[168:169], v[236:237], v[188:189]
	v_pk_fma_f32 v[172:173], v[172:173], v[230:231], v[192:193]
	v_pk_add_f32 v[182:183], v[194:195], v[198:199]

;     __device__ __forceinline__ void operator()(const f32x4 (&acc)[2][2][4][2], const Unit& u, int wr, int wc, int fr, int fq) const {
;     ...
;                             if (fq < 2) {
;                                 const f32x4* cp = (const f32x4*)(csd + pos * 16);
;                                 const f32x4 c0 = cp[0], c1 = cp[1], s0 = cp[2], s1 = cp[3];
;                                 const float cs[8] = {c0[0], c0[1], c0[2], c0[3], c1[0], c1[1], c1[2], c1[3]};
;                                 const float sn[8] = {s0[0], s0[1], s0[2], s0[3], s1[0], s1[1], s1[2], s1[3]};
;                                 const float sg = fq == 0 ? -1.f : 1.f;
; #pragma unroll
;                                 for (int e = 0; e < 8; ++e) v[e] = v[e] * cs[e] + sg * pr[e] * sn[e];
.LBB0_701:
	s_cmp_lg_u32 s45, 1
	s_cbranch_scc0 .LBB0_706
	s_andn2_b64 vcc, exec, s[86:87]
	s_cbranch_vccnz .LBB0_707
	v_and_b32_e32 v160, 64, v210
	v_xor_b32_e32 v155, 16, v210
	v_add_u32_e32 v160, 64, v160
	v_cmp_lt_i32_e32 vcc, v155, v160
	v_mov_b32_e32 v185, v3
	v_mov_b32_e32 v184, v2
	v_cndmask_b32_e32 v155, v210, v155, vcc
	v_lshlrev_b32_e32 v155, 2, v155
	ds_bpermute_b32 v192, v155, v4
	ds_bpermute_b32 v193, v155, v5
	ds_bpermute_b32 v190, v155, v6
	ds_bpermute_b32 v191, v155, v7
	ds_bpermute_b32 v188, v155, v0
	ds_bpermute_b32 v189, v155, v1
	ds_bpermute_b32 v160, v155, v2
	ds_bpermute_b32 v155, v155, v3
	v_mov_b32_e32 v181, v1
	v_mov_b32_e32 v180, v0
	v_mov_b32_e32 v177, v7
	v_mov_b32_e32 v176, v6
	v_mov_b32_e32 v171, v5
	v_mov_b32_e32 v170, v4
	s_and_saveexec_b64 s[4:5], s[6:7]
	s_cbranch_execz .LBB0_705
	v_lshl_add_u32 v170, v196, 2, s98
	ds_read_b128 v[194:197], v170
	ds_read_b128 v[222:225], v170 offset:16
	ds_read_b128 v[226:229], v170 offset:48
	ds_read_b128 v[230:233], v170 offset:32
	s_waitcnt lgkmcnt(0)
	v_cndmask_b32_e64 v160, v160, -v160, s[10:11]
	v_cndmask_b32_e64 v180, v188, -v188, s[10:11]
	v_cndmask_b32_e64 v181, v189, -v189, s[10:11]
	v_cndmask_b32_e64 v185, v155, -v155, s[10:11]
	v_cndmask_b32_e64 v170, v192, -v192, s[10:11]
	v_cndmask_b32_e64 v171, v193, -v193, s[10:11]
	v_cndmask_b32_e64 v176, v190, -v190, s[10:11]
	v_cndmask_b32_e64 v177, v191, -v191, s[10:11]
	s_waitcnt lgkmcnt(0)
	v_pk_mul_f32 v[188:189], v[6:7], v[196:197]
	v_mov_b32_e32 v184, v225
	v_mul_f32_e32 v196, v160, v228
	v_mov_b32_e32 v228, v3
	v_pk_mul_f32 v[184:185], v[228:229], v[184:185]
	v_pk_mul_f32 v[190:191], v[4:5], v[194:195]
	v_pk_mul_f32 v[192:193], v[0:1], v[222:223]
	v_mul_f32_e32 v194, v2, v224
	v_mov_b32_e32 v195, v184
	v_mov_b32_e32 v197, v185
	v_pk_fma_f32 v[170:171], v[170:171], v[230:231], v[190:191]
	v_pk_fma_f32 v[176:177], v[176:177], v[232:233], v[188:189]
	v_pk_fma_f32 v[180:181], v[180:181], v[226:227], v[192:193]
	v_pk_add_f32 v[184:185], v[194:195], v[196:197]
